# attn-proj / lru-proj tail epilogues: gate-operand loads issued before the cross-wave reduction barrier
# speedup vs baseline: 1.0023x; 1.0023x over previous
; #define LAS __attribute__((address_space(3)))
; __device__ __forceinline__ float bflo(unsigned w) { return __uint_as_float(w << 16); }
; __device__ __forceinline__ float bfhi(unsigned w) { return __uint_as_float(w & 0xffff0000u); }
; __device__ __forceinline__ u32x4 pack8(f32x4 a, f32x4 b) { u32x4 w; w.x = cvtpk(a[0], a[1]); w.y = cvtpk(a[2], a[3]); w.z = cvtpk(b[0], b[1]); w.w = cvtpk(b[2], b[3]); return w; }
; #define BAR_LDS() do { asm volatile("s_waitcnt lgkmcnt(0)" ::: "memory"); __builtin_amdgcn_s_barrier(); asm volatile("" ::: "memory"); } while (0)
; template <int EPI> __device__ __forceinline__ void tail_gemm(LAS unsigned char* lds, const bf16* Am, const bf16* Bt, int K, const TailEpi& E, int tid_in) {
;     ...
;     LAS float* part = (LAS float*)lds + (size_t)w * 64 * 65;
; #pragma unroll
;     for (int i = 0; i < 4; ++i)
; #pragma unroll
;         for (int j = 0; j < 4; ++j)
; #pragma unroll
;             for (int r = 0; r < 4; ++r) part[(16 * i + 4 * q4 + r) * 65 + 16 * j + l15] = acc[i][j][r];
;     BAR_LDS();
;     const int rl = tid >> 3, c8 = (tid & 7) * 8, row = row0 + rl, col = col0 + c8;
;     f32x4 v0 = {0.f, 0.f, 0.f, 0.f}, v1 = v0;
; #pragma unroll
;     for (int ww = 0; ww < 8; ++ww) { const LAS float* p = (const LAS float*)lds + (size_t)ww * 64 * 65 + rl * 65 + c8;
;         v0[0] += p[0]; v0[1] += p[1]; v0[2] += p[2]; v0[3] += p[3]; v1[0] += p[4]; v1[1] += p[5]; v1[2] += p[6]; v1[3] += p[7]; }
;     const size_t off = (size_t)row * 1024 + col;
;     if (EPI == 0 || EPI == 1) {
;         const u32x4 s = *(const u32x4*)(E.S + off);
;         v0[0] *= bflo(s.x); v0[1] *= bfhi(s.x); v0[2] *= bflo(s.y); v0[3] *= bfhi(s.y); v1[0] *= bflo(s.z); v1[1] *= bfhi(s.z); v1[2] *= bflo(s.w); v1[3] *= bfhi(s.w);
;         if (EPI == 1) { const u32x4 a = *(const u32x4*)(E.A + off);
;             v0[0] += bflo(a.x); v0[1] += bfhi(a.x); v0[2] += bflo(a.y); v0[3] += bfhi(a.y); v1[0] += bflo(a.z); v1[1] += bfhi(a.z); v1[2] += bflo(a.w); v1[3] += bfhi(a.w); }
;         *(u32x4*)(E.S + off) = pack8(v0, v1);
.LBB0_1315:
	s_or_b64 exec, exec, s[2:3]
	ds_write2_b32 v181, v60, v56 offset1:16
	ds_write2_b32 v181, v61, v57 offset0:65 offset1:81
	ds_write2_b32 v181, v62, v58 offset0:130 offset1:146
	ds_write2_b32 v181, v63, v59 offset0:195 offset1:211
	ds_write2_b32 v181, v44, v40 offset0:32 offset1:48
	ds_write2_b32 v181, v45, v41 offset0:97 offset1:113
	ds_write2_b32 v181, v46, v42 offset0:162 offset1:178
	ds_write2_b32 v181, v47, v43 offset0:227 offset1:243
	v_add_u32_e32 v40, 0x1000, v181
	ds_write2_b32 v40, v28, v24 offset0:16 offset1:32
	ds_write2_b32 v40, v29, v25 offset0:81 offset1:97
	ds_write2_b32 v40, v30, v26 offset0:146 offset1:162
	ds_write2_b32 v40, v31, v27 offset0:211 offset1:227
	ds_write2_b32 v40, v12, v8 offset0:48 offset1:64
	ds_write2_b32 v40, v13, v9 offset0:113 offset1:129
	ds_write2_b32 v40, v14, v10 offset0:178 offset1:194
	v_add_u32_e32 v8, 0x1200, v181
	ds_write2_b32 v8, v15, v11 offset0:115 offset1:131
	v_add_u32_e32 v8, 0x2000, v181
	ds_write2_b32 v8, v48, v52 offset0:32 offset1:48
	ds_write2_b32 v8, v49, v53 offset0:97 offset1:113
	ds_write2_b32 v8, v50, v54 offset0:162 offset1:178
	ds_write2_b32 v8, v51, v55 offset0:227 offset1:243
	ds_write2_b32 v8, v32, v36 offset0:64 offset1:80
	ds_write2_b32 v8, v33, v37 offset0:129 offset1:145
	ds_write2_b32 v8, v34, v38 offset0:194 offset1:210
	v_add_u32_e32 v8, 0x2400, v181
	ds_write2_b32 v8, v35, v39 offset0:3 offset1:19
	v_add_u32_e32 v8, 0x3000, v181
	v_add_u32_e32 v9, 0x3200, v181
	ds_write2_b32 v8, v16, v20 offset0:48 offset1:64
	ds_write2_b32 v8, v17, v21 offset0:113 offset1:129
	ds_write2_b32 v8, v18, v22 offset0:178 offset1:194
	ds_write2_b32 v9, v19, v23 offset0:115 offset1:131
	ds_write2_b32 v8, v0, v4 offset0:80 offset1:96
	ds_write2_b32 v8, v1, v5 offset0:145 offset1:161
	ds_write2_b32 v8, v2, v6 offset0:210 offset1:226
	v_add_u32_e32 v0, 0x3400, v181
	ds_write2_b32 v0, v3, v7 offset0:19 offset1:35
	v_add_u32_e32 v0, s1, v178
	v_ashrrev_i32_e32 v1, 31, v0
	v_or_b32_e32 v2, s12, v179
	v_lshlrev_b64 v[0:1], 11, v[0:1]
	v_lshl_add_u64 v[0:1], s[80:81], 0, v[0:1]
	v_lshlrev_b32_e32 v80, 1, v2
	v_lshl_add_u64 v[4:5], v[0:1], 0, v[80:81]
	global_load_dwordx4 v[0:3], v[4:5], off
	s_waitcnt lgkmcnt(0)
	s_barrier
	v_add_u32_e32 v14, 0x4100, v180
	v_add_u32_e32 v16, 0x8200, v180
	v_add_u32_e32 v18, 0xc300, v180
	ds_read2_b32 v[6:7], v180 offset1:1
	ds_read2_b32 v[8:9], v180 offset0:2 offset1:3
	ds_read2_b32 v[10:11], v180 offset0:4 offset1:5
	ds_read2_b32 v[12:13], v180 offset0:6 offset1:7
	ds_read2_b32 v[14:15], v14 offset1:1
	ds_read2_b32 v[16:17], v16 offset1:1
	ds_read2_b32 v[18:19], v18 offset1:1
	s_waitcnt lgkmcnt(6)
	v_pk_add_f32 v[6:7], v[6:7], 0 op_sel_hi:[1,0]
	v_add_u32_e32 v20, 0x4108, v180
	s_waitcnt lgkmcnt(2)
	v_pk_add_f32 v[6:7], v[6:7], v[14:15]
	ds_read2_b32 v[20:21], v20 offset1:1
	s_waitcnt lgkmcnt(2)
	v_pk_add_f32 v[6:7], v[6:7], v[16:17]
	v_pk_add_f32 v[8:9], v[8:9], 0 op_sel_hi:[1,0]
	s_waitcnt lgkmcnt(1)
	v_pk_add_f32 v[6:7], v[6:7], v[18:19]
	ds_read2_b32 v[14:15], v182 offset1:1
	ds_read2_b32 v[16:17], v190 offset1:1
	ds_read2_b32 v[18:19], v183 offset1:1
	ds_read2_b32 v[22:23], v184 offset1:1
	ds_read2_b32 v[24:25], v185 offset1:1
	s_waitcnt lgkmcnt(4)
	v_pk_add_f32 v[6:7], v[6:7], v[14:15]
	ds_read2_b32 v[14:15], v191 offset1:1
	ds_read2_b32 v[26:27], v192 offset1:1
	ds_read2_b32 v[28:29], v193 offset1:1
	s_waitcnt lgkmcnt(6)
	v_pk_add_f32 v[6:7], v[6:7], v[16:17]
	ds_read2_b32 v[16:17], v194 offset1:1
	ds_read2_b32 v[30:31], v198 offset1:1
	ds_read2_b32 v[32:33], v195 offset1:1
	ds_read2_b32 v[34:35], v196 offset1:1
	ds_read2_b32 v[36:37], v197 offset1:1
	s_waitcnt lgkmcnt(4)
	v_pk_add_f32 v[6:7], v[6:7], v[16:17]
	ds_read2_b32 v[16:17], v199 offset1:1
	ds_read2_b32 v[38:39], v200 offset1:1
	ds_read2_b32 v[40:41], v201 offset1:1
	s_waitcnt lgkmcnt(6)
	v_pk_add_f32 v[6:7], v[6:7], v[30:31]
	v_pk_add_f32 v[8:9], v[8:9], v[20:21]
	v_add_u32_e32 v44, 0x8210, v180
	s_add_i32 s0, s0, s30
	s_cmpk_gt_i32 s0, 0x9f
	s_waitcnt vmcnt(0)
	v_lshlrev_b32_e32 v30, 16, v0
	v_and_b32_e32 v31, 0xffff0000, v0
	v_pk_mul_f32 v[6:7], v[6:7], v[30:31]
	v_add_u32_e32 v0, 0x8208, v180
	v_add_u32_e32 v30, 0xc308, v180
	ds_read2_b32 v[20:21], v0 offset1:1
	ds_read2_b32 v[30:31], v30 offset1:1
	v_add_u32_e32 v0, 0x4110, v180
	ds_read2_b32 v[42:43], v0 offset1:1
	ds_read2_b32 v[44:45], v44 offset1:1
	v_lshlrev_b32_e32 v0, 16, v1
	s_waitcnt lgkmcnt(3)
	v_pk_add_f32 v[8:9], v[8:9], v[20:21]
	v_and_b32_e32 v1, 0xffff0000, v1
	s_waitcnt lgkmcnt(2)
	v_pk_add_f32 v[8:9], v[8:9], v[30:31]
	s_nop 0
	v_pk_add_f32 v[8:9], v[8:9], v[18:19]
	v_add_u32_e32 v18, 0xc318, v180
	v_pk_add_f32 v[8:9], v[8:9], v[14:15]
	v_add_u32_e32 v14, 0x4118, v180
	v_pk_add_f32 v[8:9], v[8:9], v[32:33]
	s_nop 0
	v_pk_add_f32 v[8:9], v[8:9], v[16:17]
	v_add_u32_e32 v16, 0x8218, v180
	v_pk_mul_f32 v[8:9], v[8:9], v[0:1]
	v_pk_add_f32 v[0:1], v[10:11], 0 op_sel_hi:[1,0]
	v_add_u32_e32 v10, 0xc310, v180
	ds_read2_b32 v[10:11], v10 offset1:1
	s_waitcnt lgkmcnt(2)
	v_pk_add_f32 v[0:1], v[0:1], v[42:43]
	ds_read2_b32 v[14:15], v14 offset1:1
	ds_read2_b32 v[16:17], v16 offset1:1
	ds_read2_b32 v[18:19], v18 offset1:1
	s_waitcnt lgkmcnt(4)
	v_pk_add_f32 v[0:1], v[0:1], v[44:45]
	s_waitcnt lgkmcnt(3)
	v_pk_add_f32 v[0:1], v[0:1], v[10:11]
	v_lshlrev_b32_e32 v10, 16, v2
	v_pk_add_f32 v[0:1], v[0:1], v[22:23]
	v_and_b32_e32 v11, 0xffff0000, v2
	v_pk_add_f32 v[0:1], v[0:1], v[26:27]
	v_lshlrev_b32_e32 v2, 16, v3
	v_pk_add_f32 v[0:1], v[0:1], v[34:35]
	v_and_b32_e32 v3, 0xffff0000, v3
	v_pk_add_f32 v[0:1], v[0:1], v[38:39]
	s_nop 0
	v_pk_mul_f32 v[10:11], v[0:1], v[10:11]
	v_pk_add_f32 v[0:1], v[12:13], 0 op_sel_hi:[1,0]
	s_waitcnt lgkmcnt(2)
	v_pk_add_f32 v[0:1], v[0:1], v[14:15]
	s_waitcnt lgkmcnt(1)
	v_pk_add_f32 v[0:1], v[0:1], v[16:17]
	s_waitcnt lgkmcnt(0)
	v_pk_add_f32 v[0:1], v[0:1], v[18:19]
	s_nop 0
	v_pk_add_f32 v[0:1], v[0:1], v[24:25]
	s_nop 0
	v_pk_add_f32 v[0:1], v[0:1], v[28:29]
	s_nop 0
	v_pk_add_f32 v[0:1], v[0:1], v[36:37]
	s_nop 0
	v_pk_add_f32 v[0:1], v[0:1], v[40:41]
	s_nop 0
	v_pk_mul_f32 v[12:13], v[0:1], v[2:3]
	v_cvt_pk_bf16_f32 v0, v6, v7
	v_cvt_pk_bf16_f32 v1, v8, v9
	v_cvt_pk_bf16_f32 v2, v10, v11
	v_cvt_pk_bf16_f32 v3, v12, v13
	global_store_dwordx4 v[4:5], v[0:3], off
	s_waitcnt lgkmcnt(0)
	s_barrier
	s_cbranch_scc1 .LBB0_1323

; #define LAS __attribute__((address_space(3)))
; __device__ __forceinline__ float bflo(unsigned w) { return __uint_as_float(w << 16); }
; __device__ __forceinline__ float bfhi(unsigned w) { return __uint_as_float(w & 0xffff0000u); }
; __device__ __forceinline__ u32x4 pack8(f32x4 a, f32x4 b) { u32x4 w; w.x = cvtpk(a[0], a[1]); w.y = cvtpk(a[2], a[3]); w.z = cvtpk(b[0], b[1]); w.w = cvtpk(b[2], b[3]); return w; }
; #define BAR_LDS() do { asm volatile("s_waitcnt lgkmcnt(0)" ::: "memory"); __builtin_amdgcn_s_barrier(); asm volatile("" ::: "memory"); } while (0)
; template <int EPI> __device__ __forceinline__ void tail_gemm(LAS unsigned char* lds, const bf16* Am, const bf16* Bt, int K, const TailEpi& E, int tid_in) {
;     ...
;     LAS float* part = (LAS float*)lds + (size_t)w * 64 * 65;
; #pragma unroll
;     for (int i = 0; i < 4; ++i)
; #pragma unroll
;         for (int j = 0; j < 4; ++j)
; #pragma unroll
;             for (int r = 0; r < 4; ++r) part[(16 * i + 4 * q4 + r) * 65 + 16 * j + l15] = acc[i][j][r];
;     BAR_LDS();
;     const int rl = tid >> 3, c8 = (tid & 7) * 8, row = row0 + rl, col = col0 + c8;
;     f32x4 v0 = {0.f, 0.f, 0.f, 0.f}, v1 = v0;
; #pragma unroll
;     for (int ww = 0; ww < 8; ++ww) { const LAS float* p = (const LAS float*)lds + (size_t)ww * 64 * 65 + rl * 65 + c8;
;         v0[0] += p[0]; v0[1] += p[1]; v0[2] += p[2]; v0[3] += p[3]; v1[0] += p[4]; v1[1] += p[5]; v1[2] += p[6]; v1[3] += p[7]; }
;     const size_t off = (size_t)row * 1024 + col;
;     if (EPI == 0 || EPI == 1) {
;         const u32x4 s = *(const u32x4*)(E.S + off);
;         v0[0] *= bflo(s.x); v0[1] *= bfhi(s.x); v0[2] *= bflo(s.y); v0[3] *= bfhi(s.y); v1[0] *= bflo(s.z); v1[1] *= bfhi(s.z); v1[2] *= bflo(s.w); v1[3] *= bfhi(s.w);
;         if (EPI == 1) { const u32x4 a = *(const u32x4*)(E.A + off);
;             v0[0] += bflo(a.x); v0[1] += bfhi(a.x); v0[2] += bflo(a.y); v0[3] += bfhi(a.y); v1[0] += bflo(a.z); v1[1] += bfhi(a.z); v1[2] += bflo(a.w); v1[3] += bfhi(a.w); }
;         *(u32x4*)(E.S + off) = pack8(v0, v1);
.LBB0_1350:
	s_or_b64 exec, exec, s[2:3]
	ds_write2_b32 v181, v60, v56 offset1:16
	ds_write2_b32 v181, v61, v57 offset0:65 offset1:81
	ds_write2_b32 v181, v62, v58 offset0:130 offset1:146
	ds_write2_b32 v181, v63, v59 offset0:195 offset1:211
	ds_write2_b32 v181, v44, v40 offset0:32 offset1:48
	ds_write2_b32 v181, v45, v41 offset0:97 offset1:113
	ds_write2_b32 v181, v46, v42 offset0:162 offset1:178
	ds_write2_b32 v181, v47, v43 offset0:227 offset1:243
	v_add_u32_e32 v40, 0x1000, v181
	ds_write2_b32 v40, v28, v24 offset0:16 offset1:32
	ds_write2_b32 v40, v29, v25 offset0:81 offset1:97
	ds_write2_b32 v40, v30, v26 offset0:146 offset1:162
	ds_write2_b32 v40, v31, v27 offset0:211 offset1:227
	ds_write2_b32 v40, v12, v8 offset0:48 offset1:64
	ds_write2_b32 v40, v13, v9 offset0:113 offset1:129
	ds_write2_b32 v40, v14, v10 offset0:178 offset1:194
	v_add_u32_e32 v8, 0x1200, v181
	ds_write2_b32 v8, v15, v11 offset0:115 offset1:131
	v_add_u32_e32 v8, 0x2000, v181
	ds_write2_b32 v8, v48, v52 offset0:32 offset1:48
	ds_write2_b32 v8, v49, v53 offset0:97 offset1:113
	ds_write2_b32 v8, v50, v54 offset0:162 offset1:178
	ds_write2_b32 v8, v51, v55 offset0:227 offset1:243
	ds_write2_b32 v8, v32, v36 offset0:64 offset1:80
	ds_write2_b32 v8, v33, v37 offset0:129 offset1:145
	ds_write2_b32 v8, v34, v38 offset0:194 offset1:210
	v_add_u32_e32 v8, 0x2400, v181
	ds_write2_b32 v8, v35, v39 offset0:3 offset1:19
	v_add_u32_e32 v8, 0x3000, v181
	v_add_u32_e32 v9, 0x3200, v181
	ds_write2_b32 v8, v16, v20 offset0:48 offset1:64
	ds_write2_b32 v8, v17, v21 offset0:113 offset1:129
	ds_write2_b32 v8, v18, v22 offset0:178 offset1:194
	ds_write2_b32 v9, v19, v23 offset0:115 offset1:131
	ds_write2_b32 v8, v0, v4 offset0:80 offset1:96
	ds_write2_b32 v8, v1, v5 offset0:145 offset1:161
	ds_write2_b32 v8, v2, v6 offset0:210 offset1:226
	v_add_u32_e32 v0, 0x3400, v181
	ds_write2_b32 v0, v3, v7 offset0:19 offset1:35
	v_add_u32_e32 v0, s1, v178
	v_ashrrev_i32_e32 v1, 31, v0
	v_or_b32_e32 v2, s12, v179
	v_lshlrev_b64 v[4:5], 11, v[0:1]
	v_lshl_or_b32 v4, v2, 1, v4
	v_lshl_add_u64 v[8:9], s[84:85], 0, v[4:5]
	v_lshl_add_u64 v[4:5], s[80:81], 0, v[4:5]
	global_load_dwordx4 v[0:3], v[8:9], off
	global_load_dwordx4 v[4:7], v[4:5], off
	s_waitcnt lgkmcnt(0)
	s_barrier
	v_add_u32_e32 v18, 0x4100, v180
	v_add_u32_e32 v20, 0x8200, v180
	v_add_u32_e32 v22, 0xc300, v180
	ds_read2_b32 v[10:11], v180 offset1:1
	ds_read2_b32 v[12:13], v180 offset0:2 offset1:3
	ds_read2_b32 v[14:15], v180 offset0:4 offset1:5
	ds_read2_b32 v[16:17], v180 offset0:6 offset1:7
	ds_read2_b32 v[18:19], v18 offset1:1
	ds_read2_b32 v[20:21], v20 offset1:1
	ds_read2_b32 v[22:23], v22 offset1:1
	s_waitcnt lgkmcnt(6)
	v_pk_add_f32 v[10:11], v[10:11], 0 op_sel_hi:[1,0]
	v_add_u32_e32 v24, 0x4108, v180
	s_waitcnt lgkmcnt(2)
	v_pk_add_f32 v[10:11], v[10:11], v[18:19]
	ds_read2_b32 v[24:25], v24 offset1:1
	s_waitcnt lgkmcnt(2)
	v_pk_add_f32 v[10:11], v[10:11], v[20:21]
	v_pk_add_f32 v[12:13], v[12:13], 0 op_sel_hi:[1,0]
	s_waitcnt lgkmcnt(1)
	v_pk_add_f32 v[10:11], v[10:11], v[22:23]
	ds_read2_b32 v[18:19], v182 offset1:1
	ds_read2_b32 v[20:21], v190 offset1:1
	ds_read2_b32 v[22:23], v183 offset1:1
	ds_read2_b32 v[26:27], v184 offset1:1
	ds_read2_b32 v[28:29], v185 offset1:1
	s_waitcnt lgkmcnt(4)
	v_pk_add_f32 v[10:11], v[10:11], v[18:19]
	ds_read2_b32 v[18:19], v191 offset1:1
	ds_read2_b32 v[30:31], v192 offset1:1
	ds_read2_b32 v[32:33], v193 offset1:1
	s_waitcnt lgkmcnt(6)
	v_pk_add_f32 v[10:11], v[10:11], v[20:21]
	ds_read2_b32 v[20:21], v194 offset1:1
	ds_read2_b32 v[34:35], v198 offset1:1
	ds_read2_b32 v[36:37], v195 offset1:1
	ds_read2_b32 v[38:39], v196 offset1:1
	ds_read2_b32 v[40:41], v197 offset1:1
	s_waitcnt lgkmcnt(4)
	v_pk_add_f32 v[10:11], v[10:11], v[20:21]
	ds_read2_b32 v[20:21], v199 offset1:1
	ds_read2_b32 v[42:43], v200 offset1:1
	ds_read2_b32 v[44:45], v201 offset1:1
	s_waitcnt lgkmcnt(6)
	v_pk_add_f32 v[10:11], v[10:11], v[34:35]
	v_pk_add_f32 v[12:13], v[12:13], v[24:25]
	s_add_i32 s0, s0, s30
	s_cmpk_gt_i32 s0, 0x9f
	s_waitcnt vmcnt(1)
	v_lshlrev_b32_e32 v34, 16, v0
	v_and_b32_e32 v35, 0xffff0000, v0
	s_waitcnt vmcnt(0)
	v_lshlrev_b32_e32 v46, 16, v4
	v_and_b32_e32 v47, 0xffff0000, v4
	v_add_u32_e32 v0, 0x8208, v180
	v_pk_fma_f32 v[10:11], v[10:11], v[34:35], v[46:47]
	v_add_u32_e32 v4, 0xc308, v180
	ds_read2_b32 v[24:25], v0 offset1:1
	ds_read2_b32 v[34:35], v4 offset1:1
	v_add_u32_e32 v0, 0x4110, v180
	v_add_u32_e32 v4, 0x8210, v180
	ds_read2_b32 v[46:47], v0 offset1:1
	ds_read2_b32 v[48:49], v4 offset1:1
	s_waitcnt lgkmcnt(3)
	v_pk_add_f32 v[12:13], v[12:13], v[24:25]
	v_lshlrev_b32_e32 v0, 16, v1
	s_waitcnt lgkmcnt(2)
	v_pk_add_f32 v[12:13], v[12:13], v[34:35]
	v_and_b32_e32 v1, 0xffff0000, v1
	v_pk_add_f32 v[12:13], v[12:13], v[22:23]
	v_lshlrev_b32_e32 v4, 16, v5
	v_pk_add_f32 v[12:13], v[12:13], v[18:19]
	v_and_b32_e32 v5, 0xffff0000, v5
	v_pk_add_f32 v[12:13], v[12:13], v[36:37]
	v_add_u32_e32 v18, 0x8218, v180
	v_pk_add_f32 v[12:13], v[12:13], v[20:21]
	v_add_u32_e32 v20, 0xc318, v180
	v_pk_fma_f32 v[4:5], v[12:13], v[0:1], v[4:5]
	v_add_u32_e32 v12, 0xc310, v180
	ds_read2_b32 v[12:13], v12 offset1:1
	v_pk_add_f32 v[0:1], v[14:15], 0 op_sel_hi:[1,0]
	v_add_u32_e32 v14, 0x4118, v180
	s_waitcnt lgkmcnt(2)
	v_pk_add_f32 v[0:1], v[0:1], v[46:47]
	ds_read2_b32 v[14:15], v14 offset1:1
	ds_read2_b32 v[18:19], v18 offset1:1
	ds_read2_b32 v[20:21], v20 offset1:1
	s_waitcnt lgkmcnt(4)
	v_pk_add_f32 v[0:1], v[0:1], v[48:49]
	v_lshlrev_b32_e32 v22, 16, v6
	s_waitcnt lgkmcnt(3)
	v_pk_add_f32 v[0:1], v[0:1], v[12:13]
	v_lshlrev_b32_e32 v12, 16, v2
	v_pk_add_f32 v[0:1], v[0:1], v[26:27]
	v_and_b32_e32 v13, 0xffff0000, v2
	v_pk_add_f32 v[0:1], v[0:1], v[30:31]
	v_and_b32_e32 v23, 0xffff0000, v6
	v_pk_add_f32 v[0:1], v[0:1], v[38:39]
	v_lshlrev_b32_e32 v2, 16, v3
	v_pk_add_f32 v[0:1], v[0:1], v[42:43]
	v_and_b32_e32 v3, 0xffff0000, v3
	v_pk_fma_f32 v[12:13], v[0:1], v[12:13], v[22:23]
	v_pk_add_f32 v[0:1], v[16:17], 0 op_sel_hi:[1,0]
	v_lshlrev_b32_e32 v6, 16, v7
	s_waitcnt lgkmcnt(2)
	v_pk_add_f32 v[0:1], v[0:1], v[14:15]
	v_and_b32_e32 v7, 0xffff0000, v7
	s_waitcnt lgkmcnt(1)
	v_pk_add_f32 v[0:1], v[0:1], v[18:19]
	s_waitcnt lgkmcnt(0)
	v_pk_add_f32 v[0:1], v[0:1], v[20:21]
	s_nop 0
	v_pk_add_f32 v[0:1], v[0:1], v[28:29]
	s_nop 0
	v_pk_add_f32 v[0:1], v[0:1], v[32:33]
	s_nop 0
	v_pk_add_f32 v[0:1], v[0:1], v[40:41]
	s_nop 0
	v_pk_add_f32 v[0:1], v[0:1], v[44:45]
	s_nop 0
	v_pk_fma_f32 v[6:7], v[0:1], v[2:3], v[6:7]
	v_cvt_pk_bf16_f32 v0, v10, v11
	v_cvt_pk_bf16_f32 v1, v4, v5
	v_cvt_pk_bf16_f32 v2, v12, v13
	v_cvt_pk_bf16_f32 v3, v6, v7
	global_store_dwordx4 v[8:9], v[0:3], off
	s_waitcnt lgkmcnt(0)
	s_barrier
	s_cbranch_scc1 .LBB0_1358
